# FoX: LDS-DMA issue made unconditional (sources clamped at key block 0), removing the scalar compare+branch pairs from the MFMA and softmax halves; uniform counted waits
# speedup vs baseline: 1.0092x; 1.0083x over previous
.Lfx_body:
	s_cmp_lt_u32 s62, 0x4000005e
	s_cselect_b64 s[78:79], -1, 0
	s_andn2_b64 vcc, exec, s[78:79]
	s_cbranch_vccnz .Lfx_h1_done
	s_andn2_b64 vcc, exec, s[80:81]
	s_cbranch_vccnz .Lfx_h1_qonly
	s_lshl_b32 s64, s41, 7
	s_add_i32 s66, s64, 0xffffff80
	s_max_i32 s66, s66, 0
	s_mov_b32 s67, 0
	s_lshl_b64 s[28:29], s[66:67], 8
	s_add_u32 s28, s27, s28
	s_addc_u32 s29, s38, s29
	s_lshl_b64 s[68:69], s[66:67], 2
	s_add_u32 s68, s70, s68
	s_addc_u32 s69, s71, s69
	s_add_i32 s64, s77, s51
	v_add_u32_e32 v10, s64, v183
	v_add_u32_e32 v11, s64, v184
	v_add_u32_e32 v12, s64, v185
	v_add_u32_e32 v13, s64, v186
	s_add_i32 s65, s76, s51
	v_add_u32_e32 v14, s65, v174
	s_lshl_b32 s66, s50, 2
	s_add_i32 s66, s66, s76
	v_lshl_add_u32 v0, v144, 2, s66
	v_add_u32_e32 v0, 0x10000, v0
	s_waitcnt lgkmcnt(6)
	v_mfma_f32_32x32x16_bf16 v[64:79], v[2:5], v[196:199], v[64:79]
	ds_read_b64_tr_b16 v[220:221], v11 offset:32768
	ds_read_b64_tr_b16 v[222:223], v11 offset:34816
	ds_read_b128 v[96:99], v0
	s_waitcnt lgkmcnt(7)
	v_mfma_f32_32x32x16_bf16 v[64:79], v[6:9], v[204:207], v[64:79]
	ds_read_b64_tr_b16 v[224:225], v11 offset:36864
	ds_read_b64_tr_b16 v[226:227], v11 offset:38912
	s_add_i32 s33, s73, s77
	s_mov_b32 m0, s33
	s_nop 0
	global_load_lds_dwordx4 v163, s[28:29]
	ds_read_b128 v[100:103], v0 offset:32
	s_waitcnt lgkmcnt(8)
	v_mfma_f32_32x32x16_bf16 v[64:79], v[212:215], v[200:203], v[64:79]
	ds_read_b64_tr_b16 v[228:229], v11 offset:40960
	ds_read_b64_tr_b16 v[230:231], v11 offset:43008
	ds_read_b128 v[80:83], v0 offset:128
	s_waitcnt lgkmcnt(9)
	v_mfma_f32_32x32x16_bf16 v[64:79], v[216:219], v[208:211], v[64:79]
	ds_read_b64_tr_b16 v[232:233], v11 offset:45056
	ds_read_b64_tr_b16 v[234:235], v11 offset:47104
	ds_read_b128 v[84:87], v0 offset:160
	s_waitcnt lgkmcnt(10)
	v_mfma_f32_32x32x16_bf16 v[48:63], v[220:223], v[196:199], v[48:63]
	ds_read_b64_tr_b16 v[2:3], v12 offset:32768
	ds_read_b64_tr_b16 v[4:5], v12 offset:34816
	s_add_i32 m0, s33, 0x400
	s_nop 0
	global_load_lds_dwordx4 v189, s[28:29]
	ds_read_b128 v[104:107], v0 offset:64
	s_waitcnt lgkmcnt(10)
	v_mfma_f32_32x32x16_bf16 v[48:63], v[224:227], v[204:207], v[48:63]
	ds_read_b64_tr_b16 v[6:7], v12 offset:36864
	ds_read_b64_tr_b16 v[8:9], v12 offset:38912
	ds_read_b128 v[108:111], v0 offset:96
	s_waitcnt lgkmcnt(10)
	v_mfma_f32_32x32x16_bf16 v[48:63], v[228:231], v[200:203], v[48:63]
	ds_read_b64_tr_b16 v[212:213], v12 offset:40960
	ds_read_b64_tr_b16 v[214:215], v12 offset:43008
	ds_read_b128 v[88:91], v0 offset:192
	s_waitcnt lgkmcnt(10)
	v_mfma_f32_32x32x16_bf16 v[48:63], v[232:235], v[208:211], v[48:63]
	ds_read_b64_tr_b16 v[216:217], v12 offset:45056
	ds_read_b64_tr_b16 v[218:219], v12 offset:47104
	s_add_i32 m0, s33, 0x800
	s_nop 0
	global_load_lds_dwordx4 v190, s[28:29]
	ds_read_b128 v[92:95], v0 offset:224
	s_waitcnt lgkmcnt(10)
	v_mfma_f32_32x32x16_bf16 v[32:47], v[2:5], v[196:199], v[32:47]
	ds_read_b64_tr_b16 v[220:221], v13 offset:32768
	ds_read_b64_tr_b16 v[222:223], v13 offset:34816
	s_waitcnt lgkmcnt(9)
	v_mfma_f32_32x32x16_bf16 v[32:47], v[6:9], v[204:207], v[32:47]
	ds_read_b64_tr_b16 v[224:225], v13 offset:36864
	ds_read_b64_tr_b16 v[226:227], v13 offset:38912
	s_waitcnt lgkmcnt(8)
	v_mfma_f32_32x32x16_bf16 v[32:47], v[212:215], v[200:203], v[32:47]
	ds_read_b64_tr_b16 v[228:229], v13 offset:40960
	ds_read_b64_tr_b16 v[230:231], v13 offset:43008
	s_add_i32 m0, s33, 0xc00
	s_nop 0
	global_load_lds_dwordx4 v191, s[28:29]
	s_waitcnt lgkmcnt(7)
	v_mfma_f32_32x32x16_bf16 v[32:47], v[216:219], v[208:211], v[32:47]
	ds_read_b64_tr_b16 v[232:233], v13 offset:45056
	ds_read_b64_tr_b16 v[234:235], v13 offset:47104
	s_waitcnt lgkmcnt(6)
	v_mfma_f32_32x32x16_bf16 v[16:31], v[220:223], v[196:199], v[16:31]
	v_add_u32_e32 v15, v14, v175
	ds_read_b128 v[2:5], v15
	s_waitcnt lgkmcnt(5)
	v_mfma_f32_32x32x16_bf16 v[16:31], v[224:227], v[204:207], v[16:31]
	ds_read_b128 v[6:9], v15 offset:8192
	s_add_i32 m0, s72, s77
	s_nop 0
	global_load_lds_dword v172, s[68:69]
	s_waitcnt lgkmcnt(4)
	v_mfma_f32_32x32x16_bf16 v[16:31], v[228:231], v[200:203], v[16:31]
	v_add_u32_e32 v15, v14, v176
	ds_read_b128 v[212:215], v15
	s_waitcnt lgkmcnt(3)
	v_mfma_f32_32x32x16_bf16 v[16:31], v[232:235], v[208:211], v[16:31]
	ds_read_b128 v[216:219], v15 offset:8192
	s_waitcnt lgkmcnt(3)
	v_mfma_f32_32x32x16_bf16 v[96:111], v[2:5], v[112:115], v[96:111]
	v_add_u32_e32 v15, v14, v177
	ds_read_b128 v[220:223], v15
	s_waitcnt lgkmcnt(3)
	v_mfma_f32_32x32x16_bf16 v[80:95], v[6:9], v[112:115], v[80:95]
	ds_read_b128 v[224:227], v15 offset:8192
	s_waitcnt lgkmcnt(3)
	v_mfma_f32_32x32x16_bf16 v[96:111], v[212:215], v[116:119], v[96:111]
	v_add_u32_e32 v15, v14, v178
	ds_read_b128 v[228:231], v15
	s_waitcnt lgkmcnt(3)
	v_mfma_f32_32x32x16_bf16 v[80:95], v[216:219], v[116:119], v[80:95]
	ds_read_b128 v[232:235], v15 offset:8192
	s_waitcnt lgkmcnt(3)
	v_mfma_f32_32x32x16_bf16 v[96:111], v[220:223], v[120:123], v[96:111]
	v_add_u32_e32 v15, v14, v179
	ds_read_b128 v[2:5], v15
	s_waitcnt lgkmcnt(3)
	v_mfma_f32_32x32x16_bf16 v[80:95], v[224:227], v[120:123], v[80:95]
	ds_read_b128 v[6:9], v15 offset:8192
	s_waitcnt lgkmcnt(3)
	v_mfma_f32_32x32x16_bf16 v[96:111], v[228:231], v[124:127], v[96:111]
	v_add_u32_e32 v15, v14, v180
	ds_read_b128 v[212:215], v15
	s_waitcnt lgkmcnt(3)
	v_mfma_f32_32x32x16_bf16 v[80:95], v[232:235], v[124:127], v[80:95]
	ds_read_b128 v[216:219], v15 offset:8192
	s_waitcnt lgkmcnt(3)
	v_mfma_f32_32x32x16_bf16 v[96:111], v[2:5], v[128:131], v[96:111]
	v_add_u32_e32 v15, v14, v181
	ds_read_b128 v[220:223], v15
	s_waitcnt lgkmcnt(3)
	v_mfma_f32_32x32x16_bf16 v[80:95], v[6:9], v[128:131], v[80:95]
	ds_read_b128 v[224:227], v15 offset:8192
	s_waitcnt lgkmcnt(3)
	v_mfma_f32_32x32x16_bf16 v[96:111], v[212:215], v[132:135], v[96:111]
	v_add_u32_e32 v15, v14, v182
	ds_read_b128 v[228:231], v15
	s_waitcnt lgkmcnt(3)
	v_mfma_f32_32x32x16_bf16 v[80:95], v[216:219], v[132:135], v[80:95]
	ds_read_b128 v[232:235], v15 offset:8192
	s_waitcnt lgkmcnt(0)
	s_waitcnt vmcnt(5)
	s_barrier
	v_mfma_f32_32x32x16_bf16 v[96:111], v[220:223], v[136:139], v[96:111]
	v_mfma_f32_32x32x16_bf16 v[80:95], v[224:227], v[136:139], v[80:95]
	v_mfma_f32_32x32x16_bf16 v[96:111], v[228:231], v[140:143], v[96:111]
	v_mfma_f32_32x32x16_bf16 v[80:95], v[232:235], v[140:143], v[80:95]
	s_nop 7
	s_branch .Lfx_h1_joined
.Lfx_h1_qonly:
	s_lshl_b32 s64, s41, 7
	s_add_i32 s66, s64, 0xffffff80
	s_max_i32 s66, s66, 0
	s_mov_b32 s67, 0
	s_lshl_b64 s[28:29], s[66:67], 8
	s_add_u32 s28, s27, s28
	s_addc_u32 s29, s38, s29
	s_lshl_b64 s[68:69], s[66:67], 2
	s_add_u32 s68, s70, s68
	s_addc_u32 s69, s71, s69
	s_add_i32 s65, s76, s51
	v_add_u32_e32 v14, s65, v174
	s_lshl_b32 s66, s50, 2
	s_add_i32 s66, s66, s76
	v_lshl_add_u32 v0, v144, 2, s66
	v_add_u32_e32 v0, 0x10000, v0
	ds_read_b128 v[96:99], v0
	ds_read_b128 v[100:103], v0 offset:32
	ds_read_b128 v[80:83], v0 offset:128
	ds_read_b128 v[84:87], v0 offset:160
	ds_read_b128 v[104:107], v0 offset:64
	ds_read_b128 v[108:111], v0 offset:96
	ds_read_b128 v[88:91], v0 offset:192
	ds_read_b128 v[92:95], v0 offset:224
	v_add_u32_e32 v15, v14, v175
	ds_read_b128 v[2:5], v15
	ds_read_b128 v[6:9], v15 offset:8192
	v_add_u32_e32 v15, v14, v176
	ds_read_b128 v[212:215], v15
	ds_read_b128 v[216:219], v15 offset:8192
	s_waitcnt lgkmcnt(3)
	v_mfma_f32_32x32x16_bf16 v[96:111], v[2:5], v[112:115], v[96:111]
	v_add_u32_e32 v15, v14, v177
	ds_read_b128 v[220:223], v15
	s_waitcnt lgkmcnt(3)
	v_mfma_f32_32x32x16_bf16 v[80:95], v[6:9], v[112:115], v[80:95]
	ds_read_b128 v[224:227], v15 offset:8192
	s_add_i32 s33, s73, s77
	s_mov_b32 m0, s33
	s_nop 0
	global_load_lds_dwordx4 v163, s[28:29]
	s_waitcnt lgkmcnt(3)
	v_mfma_f32_32x32x16_bf16 v[96:111], v[212:215], v[116:119], v[96:111]
	v_add_u32_e32 v15, v14, v178
	ds_read_b128 v[228:231], v15
	s_waitcnt lgkmcnt(3)
	v_mfma_f32_32x32x16_bf16 v[80:95], v[216:219], v[116:119], v[80:95]
	ds_read_b128 v[232:235], v15 offset:8192
	s_add_i32 m0, s33, 0x400
	s_nop 0
	global_load_lds_dwordx4 v189, s[28:29]
	s_waitcnt lgkmcnt(3)
	v_mfma_f32_32x32x16_bf16 v[96:111], v[220:223], v[120:123], v[96:111]
	v_add_u32_e32 v15, v14, v179
	ds_read_b128 v[2:5], v15
	s_waitcnt lgkmcnt(3)
	v_mfma_f32_32x32x16_bf16 v[80:95], v[224:227], v[120:123], v[80:95]
	ds_read_b128 v[6:9], v15 offset:8192
	s_add_i32 m0, s33, 0x800
	s_nop 0
	global_load_lds_dwordx4 v190, s[28:29]
	s_waitcnt lgkmcnt(3)
	v_mfma_f32_32x32x16_bf16 v[96:111], v[228:231], v[124:127], v[96:111]
	v_add_u32_e32 v15, v14, v180
	ds_read_b128 v[212:215], v15
	s_waitcnt lgkmcnt(3)
	v_mfma_f32_32x32x16_bf16 v[80:95], v[232:235], v[124:127], v[80:95]
	ds_read_b128 v[216:219], v15 offset:8192
	s_add_i32 m0, s33, 0xc00
	s_nop 0
	global_load_lds_dwordx4 v191, s[28:29]
	s_waitcnt lgkmcnt(3)
	v_mfma_f32_32x32x16_bf16 v[96:111], v[2:5], v[128:131], v[96:111]
	v_add_u32_e32 v15, v14, v181
	ds_read_b128 v[220:223], v15
	s_waitcnt lgkmcnt(3)
	v_mfma_f32_32x32x16_bf16 v[80:95], v[6:9], v[128:131], v[80:95]
	ds_read_b128 v[224:227], v15 offset:8192
	s_add_i32 m0, s72, s77
	s_nop 0
	global_load_lds_dword v172, s[68:69]
	s_waitcnt lgkmcnt(3)
	v_mfma_f32_32x32x16_bf16 v[96:111], v[212:215], v[132:135], v[96:111]
	v_add_u32_e32 v15, v14, v182
	ds_read_b128 v[228:231], v15
	s_waitcnt lgkmcnt(3)
	v_mfma_f32_32x32x16_bf16 v[80:95], v[216:219], v[132:135], v[80:95]
	ds_read_b128 v[232:235], v15 offset:8192
	s_waitcnt lgkmcnt(0)
	s_waitcnt vmcnt(5)
	s_barrier
	v_mfma_f32_32x32x16_bf16 v[96:111], v[220:223], v[136:139], v[96:111]
	v_mfma_f32_32x32x16_bf16 v[80:95], v[224:227], v[136:139], v[80:95]
	v_mfma_f32_32x32x16_bf16 v[96:111], v[228:231], v[140:143], v[96:111]
	v_mfma_f32_32x32x16_bf16 v[80:95], v[232:235], v[140:143], v[80:95]
	s_add_i32 s29, s62, 0xc0000001
	s_cmp_gt_u32 s29, 0xc000005d
	s_cbranch_scc1 .Lfx_nomask_q
	s_nop 11
	v_add_u32_e32 v0, s62, v147
	v_subrev_u32_e32 v2, 30, v0
	v_cmp_gt_u32_e32 vcc, 2.0, v2
	v_add_u32_e32 v2, 0xbfffffc2, v0
	s_nop 3
	v_cndmask_b32_e32 v96, v187, v96, vcc
	v_cmp_lt_u32_e32 vcc, s17, v2
	v_subrev_u32_e32 v2, 31, v0
	s_nop 0
	v_cndmask_b32_e32 v80, v187, v80, vcc
	v_cmp_gt_u32_e32 vcc, 2.0, v2
	v_add_u32_e32 v2, 0xbfffffc1, v0
	s_nop 0
	v_cndmask_b32_e32 v97, v187, v97, vcc
	v_cmp_lt_u32_e32 vcc, s17, v2
	v_subrev_u32_e32 v2, 32, v0
	s_nop 0
	v_cndmask_b32_e32 v81, v187, v81, vcc
	v_cmp_gt_u32_e32 vcc, 2.0, v2
	v_add_u32_e32 v2, 0xbfffffc0, v0
	s_nop 0
	v_cndmask_b32_e32 v98, v187, v98, vcc
	v_cmp_lt_u32_e32 vcc, s17, v2
	v_subrev_u32_e32 v2, 33, v0
	s_nop 0
	v_cndmask_b32_e32 v82, v187, v82, vcc
	v_cmp_gt_u32_e32 vcc, 2.0, v2
	v_add_u32_e32 v2, 0xbfffffbf, v0
	s_nop 0
	v_cndmask_b32_e32 v99, v187, v99, vcc
	v_cmp_lt_u32_e32 vcc, s17, v2
	v_subrev_u32_e32 v2, 38, v0
	s_nop 0
	v_cndmask_b32_e32 v83, v187, v83, vcc
	v_cmp_gt_u32_e32 vcc, 2.0, v2
	v_add_u32_e32 v2, 0xbfffffba, v0
	s_nop 0
	v_cndmask_b32_e32 v100, v187, v100, vcc
	v_cmp_lt_u32_e32 vcc, s17, v2
	v_subrev_u32_e32 v2, 39, v0
	s_nop 0
	v_cndmask_b32_e32 v84, v187, v84, vcc
	v_cmp_gt_u32_e32 vcc, 2.0, v2
	v_add_u32_e32 v2, 0xbfffffb9, v0
	s_nop 0
	v_cndmask_b32_e32 v101, v187, v101, vcc
	v_cmp_lt_u32_e32 vcc, s17, v2
	v_subrev_u32_e32 v2, 40, v0
	s_nop 0
	v_cndmask_b32_e32 v85, v187, v85, vcc
	v_cmp_gt_u32_e32 vcc, 2.0, v2
	v_add_u32_e32 v2, 0xbfffffb8, v0
	s_nop 0
	v_cndmask_b32_e32 v102, v187, v102, vcc
	v_cmp_lt_u32_e32 vcc, s17, v2
	v_subrev_u32_e32 v2, 41, v0
	s_nop 0
	v_cndmask_b32_e32 v86, v187, v86, vcc
	v_cmp_gt_u32_e32 vcc, 2.0, v2
	v_add_u32_e32 v2, 0xbfffffb7, v0
	s_nop 0
	v_cndmask_b32_e32 v103, v187, v103, vcc
	v_cmp_lt_u32_e32 vcc, s17, v2
	v_subrev_u32_e32 v2, 46, v0
	s_nop 0
	v_cndmask_b32_e32 v87, v187, v87, vcc
	v_cmp_gt_u32_e32 vcc, 2.0, v2
	v_add_u32_e32 v2, 0xbfffffb2, v0
	s_nop 0
	v_cndmask_b32_e32 v104, v187, v104, vcc
	v_cmp_lt_u32_e32 vcc, s17, v2
	v_subrev_u32_e32 v2, 47, v0
	s_nop 0
	v_cndmask_b32_e32 v88, v187, v88, vcc
	v_cmp_gt_u32_e32 vcc, 2.0, v2
	v_add_u32_e32 v2, 0xbfffffb1, v0
	s_nop 0
	v_cndmask_b32_e32 v105, v187, v105, vcc
	v_cmp_lt_u32_e32 vcc, s17, v2
	v_subrev_u32_e32 v2, 48, v0
	s_nop 0
	v_cndmask_b32_e32 v89, v187, v89, vcc
	v_cmp_gt_u32_e32 vcc, 2.0, v2
	v_add_u32_e32 v2, 0xbfffffb0, v0
	s_nop 0
	v_cndmask_b32_e32 v106, v187, v106, vcc
	v_cmp_lt_u32_e32 vcc, s17, v2
	v_subrev_u32_e32 v2, 49, v0
	s_nop 0
	v_cndmask_b32_e32 v90, v187, v90, vcc
	v_cmp_gt_u32_e32 vcc, 2.0, v2
	v_add_u32_e32 v2, 0xbfffffaf, v0
	s_nop 0
	v_cndmask_b32_e32 v107, v187, v107, vcc
	v_cmp_lt_u32_e32 vcc, s17, v2
	v_subrev_u32_e32 v2, 54, v0
	s_nop 0
	v_cndmask_b32_e32 v91, v187, v91, vcc
	v_cmp_gt_u32_e32 vcc, 2.0, v2
	v_add_u32_e32 v2, 0xbfffffaa, v0
	s_nop 0
	v_cndmask_b32_e32 v108, v187, v108, vcc
	v_cmp_lt_u32_e32 vcc, s17, v2
	v_subrev_u32_e32 v2, 55, v0
	s_nop 0
	v_cndmask_b32_e32 v92, v187, v92, vcc
	v_cmp_gt_u32_e32 vcc, 2.0, v2
	v_add_u32_e32 v2, 0xbfffffa9, v0
	s_nop 0
	v_cndmask_b32_e32 v109, v187, v109, vcc
	v_cmp_lt_u32_e32 vcc, s17, v2
	v_subrev_u32_e32 v2, 56, v0
	s_nop 0
	v_cndmask_b32_e32 v93, v187, v93, vcc
	v_cmp_gt_u32_e32 vcc, 2.0, v2
	v_add_u32_e32 v2, 0xbfffffa8, v0
	s_nop 0
	v_cndmask_b32_e32 v110, v187, v110, vcc
	v_cmp_lt_u32_e32 vcc, s17, v2
	v_subrev_u32_e32 v2, 57, v0
	v_add_u32_e32 v0, 0xbfffffa7, v0
	v_cndmask_b32_e32 v94, v187, v94, vcc
	v_cmp_gt_u32_e32 vcc, 2.0, v2
	s_nop 1
	v_cndmask_b32_e32 v111, v187, v111, vcc
	v_cmp_lt_u32_e32 vcc, s17, v0
	s_nop 1
	v_cndmask_b32_e32 v95, v187, v95, vcc

.Lfx_h1_joined:
	s_andn2_b64 vcc, exec, s[78:79]
	s_cbranch_vccnz .Lfx_h2_invis
	s_lshl_b32 s64, s41, 7
	s_add_i32 s66, s64, 0xffffff80
	s_max_i32 s66, s66, 0
	s_mov_b32 s67, 0
	s_lshl_b64 s[30:31], s[66:67], 8
	s_add_u32 s30, s23, s30
	s_addc_u32 s31, s24, s31
	s_add_i32 m0, s74, s77
	s_nop 0
	global_load_lds_dwordx4 v188, s[30:31]
	s_nop 3
	v_max3_f32 v0, v96, v97, v80
	v_max3_f32 v2, v98, v99, v81
	v_max3_f32 v0, v0, v82, v83
	v_max3_f32 v2, v2, v102, v103
	v_max3_f32 v0, v0, v100, v101
	v_max3_f32 v2, v2, v86, v87
	v_max3_f32 v0, v0, v84, v85
	v_max3_f32 v2, v2, v106, v107
	v_max3_f32 v0, v0, v104, v105
	v_max3_f32 v2, v2, v90, v91
	v_max3_f32 v0, v0, v88, v89
	v_max3_f32 v2, v2, v110, v111
	v_max3_f32 v0, v0, v108, v109
	v_max3_f32 v2, v2, v94, v95
	v_max3_f32 v0, v0, v92, v93
	v_max_f32_e32 v2, v2, v2
	v_max_f32_e32 v0, v0, v0
	v_max_f32_e32 v0, v0, v2
	v_mov_b32_e32 v2, v0
	s_nop 1
	v_permlane32_swap_b32_e32 v0, v2
	v_max_f32_e32 v2, v2, v2
	v_max_f32_e32 v0, v0, v0
	v_max_f32_e32 v0, v0, v2
	v_add_f32_e32 v2, 0x41000000, v192
	v_cmp_gt_f32_e32 vcc, v0, v2
	s_cbranch_vccz .Lfx_sm_exp_v
	v_max_f32_e32 v0, v0, v0
	v_max_f32_e32 v2, v192, v192
	v_max_f32_e32 v2, v2, v0
	v_sub_f32_e32 v0, v192, v2
	v_exp_f32_e32 v0, v0
	v_mov_b32_e32 v192, v2
	v_mul_f32_e32 v162, v162, v0
	v_pk_mul_f32 v[78:79], v[78:79], v[0:1] op_sel_hi:[1,0]
	v_pk_mul_f32 v[76:77], v[76:77], v[0:1] op_sel_hi:[1,0]
	v_pk_mul_f32 v[74:75], v[74:75], v[0:1] op_sel_hi:[1,0]
	v_pk_mul_f32 v[72:73], v[72:73], v[0:1] op_sel_hi:[1,0]
	v_pk_mul_f32 v[70:71], v[70:71], v[0:1] op_sel_hi:[1,0]
	v_pk_mul_f32 v[68:69], v[68:69], v[0:1] op_sel_hi:[1,0]
	v_pk_mul_f32 v[66:67], v[66:67], v[0:1] op_sel_hi:[1,0]
	v_pk_mul_f32 v[64:65], v[64:65], v[0:1] op_sel_hi:[1,0]
	v_pk_mul_f32 v[62:63], v[62:63], v[0:1] op_sel_hi:[1,0]
	v_pk_mul_f32 v[60:61], v[60:61], v[0:1] op_sel_hi:[1,0]
	v_pk_mul_f32 v[58:59], v[58:59], v[0:1] op_sel_hi:[1,0]
	v_pk_mul_f32 v[56:57], v[56:57], v[0:1] op_sel_hi:[1,0]
	v_pk_mul_f32 v[54:55], v[54:55], v[0:1] op_sel_hi:[1,0]
	v_pk_mul_f32 v[52:53], v[52:53], v[0:1] op_sel_hi:[1,0]
	v_pk_mul_f32 v[50:51], v[50:51], v[0:1] op_sel_hi:[1,0]
	v_pk_mul_f32 v[48:49], v[48:49], v[0:1] op_sel_hi:[1,0]
	v_pk_mul_f32 v[46:47], v[46:47], v[0:1] op_sel_hi:[1,0]
	v_pk_mul_f32 v[44:45], v[44:45], v[0:1] op_sel_hi:[1,0]
	v_pk_mul_f32 v[42:43], v[42:43], v[0:1] op_sel_hi:[1,0]
	v_pk_mul_f32 v[40:41], v[40:41], v[0:1] op_sel_hi:[1,0]
	v_pk_mul_f32 v[38:39], v[38:39], v[0:1] op_sel_hi:[1,0]
	v_pk_mul_f32 v[36:37], v[36:37], v[0:1] op_sel_hi:[1,0]
	v_pk_mul_f32 v[34:35], v[34:35], v[0:1] op_sel_hi:[1,0]
	v_pk_mul_f32 v[32:33], v[32:33], v[0:1] op_sel_hi:[1,0]
	v_pk_mul_f32 v[30:31], v[30:31], v[0:1] op_sel_hi:[1,0]
	v_pk_mul_f32 v[28:29], v[28:29], v[0:1] op_sel_hi:[1,0]
	v_pk_mul_f32 v[26:27], v[26:27], v[0:1] op_sel_hi:[1,0]
	v_pk_mul_f32 v[24:25], v[24:25], v[0:1] op_sel_hi:[1,0]
	v_pk_mul_f32 v[22:23], v[22:23], v[0:1] op_sel_hi:[1,0]
	v_pk_mul_f32 v[20:21], v[20:21], v[0:1] op_sel_hi:[1,0]
	v_pk_mul_f32 v[18:19], v[18:19], v[0:1] op_sel_hi:[1,0]
	v_pk_mul_f32 v[16:17], v[16:17], v[0:1] op_sel_hi:[1,0]
.Lfx_sm_exp_v:
	v_sub_f32_e32 v0, v96, v192
	v_exp_f32_e32 v193, v0
	v_sub_f32_e32 v0, v80, v192
	v_exp_f32_e32 v194, v0
	v_sub_f32_e32 v0, v97, v192
	global_load_lds_dwordx4 v188, s[30:31] offset:1024
	v_exp_f32_e32 v2, v0
	v_sub_f32_e32 v0, v81, v192
	v_exp_f32_e32 v0, v0
	v_add_f32_e32 v3, v193, v194
	v_add_f32_e32 v4, v2, v0
	v_add_f32_e32 v5, v3, v1
	s_nop 0
	v_add_f32_e32 v9, v4, v5
	v_sub_f32_e32 v3, v98, v192
	v_sub_f32_e32 v4, v82, v192
	v_exp_f32_e32 v3, v3
	v_exp_f32_e32 v98, v4
	v_sub_f32_e32 v4, v99, v192
	v_sub_f32_e32 v5, v83, v192
	v_exp_f32_e32 v4, v4
	v_exp_f32_e32 v8, v5
	v_add_f32_e32 v5, v3, v98
	v_cvt_pk_bf16_f32 v196, v193, v2
	v_cvt_pk_bf16_f32 v197, v3, v4
	v_add_f32_e32 v6, v4, v8
	v_add_f32_e32 v7, v5, v9
	v_sub_f32_e32 v5, v100, v192
	v_add_f32_e32 v11, v6, v7
	v_sub_f32_e32 v6, v84, v192
	v_exp_f32_e32 v5, v5
	v_exp_f32_e32 v9, v6
	v_sub_f32_e32 v6, v101, v192
	v_sub_f32_e32 v7, v85, v192
	v_exp_f32_e32 v6, v6
	v_exp_f32_e32 v10, v7
	global_load_lds_dwordx4 v188, s[30:31] offset:2048
	v_add_f32_e32 v7, v5, v9
	v_cvt_pk_bf16_f32 v198, v5, v6
	v_add_f32_e32 v12, v6, v10
	v_add_f32_e32 v13, v7, v11
	v_sub_f32_e32 v7, v102, v192
	v_add_f32_e32 v13, v12, v13
	v_sub_f32_e32 v11, v86, v192
	v_sub_f32_e32 v12, v103, v192
	v_exp_f32_e32 v7, v7
	v_exp_f32_e32 v11, v11
	v_exp_f32_e32 v14, v12
	v_sub_f32_e32 v12, v87, v192
	v_exp_f32_e32 v12, v12
	v_add_f32_e32 v15, v7, v11
	v_cvt_pk_bf16_f32 v199, v7, v14
	v_cvt_pk_bf16_f32 v200, v194, v0
	v_add_f32_e32 v80, v14, v12
	v_add_f32_e32 v81, v15, v13
	v_sub_f32_e32 v13, v104, v192
	v_add_f32_e32 v81, v80, v81
	v_sub_f32_e32 v15, v88, v192
	v_sub_f32_e32 v80, v105, v192
	v_exp_f32_e32 v13, v13
	v_exp_f32_e32 v15, v15
	v_exp_f32_e32 v82, v80
	v_sub_f32_e32 v80, v89, v192
	v_exp_f32_e32 v80, v80
	v_add_f32_e32 v83, v13, v15
	v_cvt_pk_bf16_f32 v201, v98, v8
	v_cvt_pk_bf16_f32 v202, v9, v10
	global_load_lds_dwordx4 v188, s[30:31] offset:3072
	v_add_f32_e32 v84, v82, v80
	v_add_f32_e32 v85, v83, v81
	v_sub_f32_e32 v81, v106, v192
	v_add_f32_e32 v85, v84, v85
	v_sub_f32_e32 v83, v90, v192
	v_sub_f32_e32 v84, v107, v192
	v_exp_f32_e32 v81, v81
	v_exp_f32_e32 v83, v83
	v_exp_f32_e32 v86, v84
	v_sub_f32_e32 v84, v91, v192
	v_exp_f32_e32 v84, v84
	v_add_f32_e32 v87, v81, v83
	v_cvt_pk_bf16_f32 v203, v11, v12
	v_cvt_pk_bf16_f32 v204, v13, v82
	v_add_f32_e32 v88, v86, v84
	v_add_f32_e32 v89, v87, v85
	v_sub_f32_e32 v85, v108, v192
	v_add_f32_e32 v89, v88, v89
	v_sub_f32_e32 v87, v92, v192
	v_sub_f32_e32 v88, v109, v192
	v_exp_f32_e32 v85, v85
	v_exp_f32_e32 v87, v87
	v_exp_f32_e32 v90, v88
	v_sub_f32_e32 v88, v93, v192
	v_exp_f32_e32 v88, v88
	v_add_f32_e32 v91, v85, v87
	v_cvt_pk_bf16_f32 v205, v81, v86
	v_cvt_pk_bf16_f32 v206, v85, v90
	v_add_f32_e32 v92, v90, v88
	v_add_f32_e32 v93, v91, v89
	v_sub_f32_e32 v89, v110, v192
	v_add_f32_e32 v93, v92, v93
	v_sub_f32_e32 v91, v94, v192
	v_sub_f32_e32 v92, v111, v192
	v_exp_f32_e32 v89, v89
	v_exp_f32_e32 v91, v91
	v_exp_f32_e32 v94, v92
	v_sub_f32_e32 v92, v95, v192
	v_exp_f32_e32 v92, v92
	v_add_f32_e32 v95, v89, v91
	v_cvt_pk_bf16_f32 v207, v89, v94
	v_cvt_pk_bf16_f32 v208, v15, v80
	v_add_f32_e32 v96, v94, v92
	v_add_f32_e32 v97, v95, v93
	v_cvt_pk_bf16_f32 v209, v83, v84
	v_add_f32_e32 v93, v96, v97
	v_add_f32_e32 v162, v162, v93
	v_cvt_pk_bf16_f32 v210, v87, v88
	v_cvt_pk_bf16_f32 v211, v91, v92
	s_waitcnt vmcnt(4)
	s_add_i32 s64, s76, s51
	v_add_u32_e32 v10, s64, v183
	ds_read_b64_tr_b16 v[2:3], v10 offset:32768
	ds_read_b64_tr_b16 v[4:5], v10 offset:34816
	ds_read_b64_tr_b16 v[6:7], v10 offset:36864
	ds_read_b64_tr_b16 v[8:9], v10 offset:38912
	ds_read_b64_tr_b16 v[212:213], v10 offset:40960
	ds_read_b64_tr_b16 v[214:215], v10 offset:43008
	ds_read_b64_tr_b16 v[216:217], v10 offset:45056
	ds_read_b64_tr_b16 v[218:219], v10 offset:47104
	s_branch .Lfx_h2_done
.Lfx_h2_invis:
	s_lshl_b32 s64, s41, 7
	s_add_i32 s66, s64, 0xffffff80
	s_max_i32 s66, s66, 0
	s_mov_b32 s67, 0
	s_lshl_b64 s[30:31], s[66:67], 8
	s_add_u32 s30, s23, s30
	s_addc_u32 s31, s24, s31
	s_add_i32 m0, s74, s77
	s_nop 0
	global_load_lds_dwordx4 v188, s[30:31]
	global_load_lds_dwordx4 v188, s[30:31] offset:1024
	global_load_lds_dwordx4 v188, s[30:31] offset:2048
	global_load_lds_dwordx4 v188, s[30:31] offset:3072
	s_waitcnt vmcnt(4)
.Lfx_h2_done:
	s_barrier
	s_add_i32 s63, s63, 1
	s_add_i32 s41, s41, -1
	s_addk_i32 s62, 0x80
	s_xor_b32 s76, s76, 0x10200
	s_xor_b32 s77, s77, 0x10200
	s_mov_b64 s[80:81], s[78:79]
	s_cmp_eq_u32 s41, -1
	s_cbranch_scc0 .Lfx_body
	s_andn2_b64 vcc, exec, s[80:81]
	s_cbranch_vccnz .Lfx_tail_skip
	s_add_i32 s64, s77, s51
	v_add_u32_e32 v10, s64, v183
	v_add_u32_e32 v11, s64, v184
	v_add_u32_e32 v12, s64, v185
	v_add_u32_e32 v13, s64, v186
	s_waitcnt lgkmcnt(6)
	v_mfma_f32_32x32x16_bf16 v[64:79], v[2:5], v[196:199], v[64:79]
	ds_read_b64_tr_b16 v[220:221], v11 offset:32768
	ds_read_b64_tr_b16 v[222:223], v11 offset:34816
	s_waitcnt lgkmcnt(6)
	v_mfma_f32_32x32x16_bf16 v[64:79], v[6:9], v[204:207], v[64:79]
	ds_read_b64_tr_b16 v[224:225], v11 offset:36864
	ds_read_b64_tr_b16 v[226:227], v11 offset:38912
	s_waitcnt lgkmcnt(6)
	v_mfma_f32_32x32x16_bf16 v[64:79], v[212:215], v[200:203], v[64:79]
	ds_read_b64_tr_b16 v[228:229], v11 offset:40960
	ds_read_b64_tr_b16 v[230:231], v11 offset:43008
	s_waitcnt lgkmcnt(6)
	v_mfma_f32_32x32x16_bf16 v[64:79], v[216:219], v[208:211], v[64:79]
	ds_read_b64_tr_b16 v[232:233], v11 offset:45056
	ds_read_b64_tr_b16 v[234:235], v11 offset:47104
	s_waitcnt lgkmcnt(6)
	v_mfma_f32_32x32x16_bf16 v[48:63], v[220:223], v[196:199], v[48:63]
	ds_read_b64_tr_b16 v[2:3], v12 offset:32768
	ds_read_b64_tr_b16 v[4:5], v12 offset:34816
	s_waitcnt lgkmcnt(6)
	v_mfma_f32_32x32x16_bf16 v[48:63], v[224:227], v[204:207], v[48:63]
	ds_read_b64_tr_b16 v[6:7], v12 offset:36864
	ds_read_b64_tr_b16 v[8:9], v12 offset:38912
	s_waitcnt lgkmcnt(6)
	v_mfma_f32_32x32x16_bf16 v[48:63], v[228:231], v[200:203], v[48:63]
	ds_read_b64_tr_b16 v[212:213], v12 offset:40960
	ds_read_b64_tr_b16 v[214:215], v12 offset:43008
	s_waitcnt lgkmcnt(6)
	v_mfma_f32_32x32x16_bf16 v[48:63], v[232:235], v[208:211], v[48:63]
	ds_read_b64_tr_b16 v[216:217], v12 offset:45056
	ds_read_b64_tr_b16 v[218:219], v12 offset:47104
	s_waitcnt lgkmcnt(6)
	v_mfma_f32_32x32x16_bf16 v[32:47], v[2:5], v[196:199], v[32:47]
	ds_read_b64_tr_b16 v[220:221], v13 offset:32768
	ds_read_b64_tr_b16 v[222:223], v13 offset:34816
	s_waitcnt lgkmcnt(6)
	v_mfma_f32_32x32x16_bf16 v[32:47], v[6:9], v[204:207], v[32:47]
	ds_read_b64_tr_b16 v[224:225], v13 offset:36864
	ds_read_b64_tr_b16 v[226:227], v13 offset:38912
	s_waitcnt lgkmcnt(6)
	v_mfma_f32_32x32x16_bf16 v[32:47], v[212:215], v[200:203], v[32:47]
	ds_read_b64_tr_b16 v[228:229], v13 offset:40960
	ds_read_b64_tr_b16 v[230:231], v13 offset:43008
	s_waitcnt lgkmcnt(6)
	v_mfma_f32_32x32x16_bf16 v[32:47], v[216:219], v[208:211], v[32:47]
	ds_read_b64_tr_b16 v[232:233], v13 offset:45056
	ds_read_b64_tr_b16 v[234:235], v13 offset:47104
	s_waitcnt lgkmcnt(6)
	v_mfma_f32_32x32x16_bf16 v[16:31], v[220:223], v[196:199], v[16:31]
	s_waitcnt lgkmcnt(4)
	v_mfma_f32_32x32x16_bf16 v[16:31], v[224:227], v[204:207], v[16:31]
	s_waitcnt lgkmcnt(2)
	v_mfma_f32_32x32x16_bf16 v[16:31], v[228:231], v[200:203], v[16:31]
	s_waitcnt lgkmcnt(0)
	v_mfma_f32_32x32x16_bf16 v[16:31], v[232:235], v[208:211], v[16:31]
	s_waitcnt vmcnt(0)
.Lfx_tail_skip:
	s_waitcnt vmcnt(0)
.Lfx_tail_done:
	s_cmp_lg_u32 s42, 0
	s_cbranch_scc1 .Lfx_nogp
	v_lshlrev_b64 v[236:237], 11, v[160:161]
	v_lshl_add_u64 v[236:237], v[156:157], 0, v[236:237]
	global_load_dwordx2 v[196:197], v[236:237], off
	global_load_dwordx2 v[198:199], v[236:237], off offset:16
	global_load_dwordx2 v[200:201], v[236:237], off offset:32
	global_load_dwordx2 v[202:203], v[236:237], off offset:48
	global_load_dwordx2 v[204:205], v[236:237], off offset:64
	global_load_dwordx2 v[206:207], v[236:237], off offset:80
	global_load_dwordx2 v[208:209], v[236:237], off offset:96
	global_load_dwordx2 v[210:211], v[236:237], off offset:112
	global_load_dwordx2 v[212:213], v[236:237], off offset:128
	global_load_dwordx2 v[214:215], v[236:237], off offset:144
	global_load_dwordx2 v[216:217], v[236:237], off offset:160
	global_load_dwordx2 v[218:219], v[236:237], off offset:176
	global_load_dwordx2 v[220:221], v[236:237], off offset:192
	global_load_dwordx2 v[222:223], v[236:237], off offset:208
	global_load_dwordx2 v[224:225], v[236:237], off offset:224
	global_load_dwordx2 v[226:227], v[236:237], off offset:240
